# dn_prep X_bot: 128 serialized LDS round trips per thread replaced by batched, double-buffered b128 broadcast reads (Z row stride 36 floats); same FMA order
# speedup vs baseline: 1.0274x; 1.0134x over previous
; DI void dn_prep_item(const Params& p, int l, int item, int next_item, u32x4 (&pre)[12], unsigned char* lds, int tid) {
;     ...
;             } else if (lane < 32) {
; #pragma unroll
;                 for (int i = 0; i < 32; ++i) Zs[i * 33 + c] = x[i];
;             }
.LBB0_498:
	s_andn2_saveexec_b64 s[6:7], s[6:7]
	s_cbranch_execz .LBB0_502
	v_cmp_gt_u32_e32 vcc, 32, v30
	s_and_saveexec_b64 s[10:11], vcc
	s_cbranch_execz .LBB0_501
	v_lshl_add_u32 v30, v31, 2, v52
	ds_write_b32 v30, v0
	ds_write_b32 v30, v1 offset:144
	ds_write_b32 v30, v2 offset:288
	ds_write_b32 v30, v3 offset:432
	ds_write_b32 v30, v4 offset:576
	ds_write_b32 v30, v5 offset:720
	ds_write_b32 v30, v6 offset:864
	ds_write_b32 v30, v7 offset:1008
	ds_write_b32 v30, v8 offset:1152
	ds_write_b32 v30, v9 offset:1296
	ds_write_b32 v30, v10 offset:1440
	ds_write_b32 v30, v11 offset:1584
	ds_write_b32 v30, v12 offset:1728
	ds_write_b32 v30, v13 offset:1872
	ds_write_b32 v30, v14 offset:2016
	ds_write_b32 v30, v15 offset:2160
	ds_write_b32 v30, v16 offset:2304
	ds_write_b32 v30, v17 offset:2448
	ds_write_b32 v30, v18 offset:2592
	ds_write_b32 v30, v19 offset:2736
	ds_write_b32 v30, v20 offset:2880
	ds_write_b32 v30, v21 offset:3024
	ds_write_b32 v30, v22 offset:3168
	ds_write_b32 v30, v23 offset:3312
	ds_write_b32 v30, v24 offset:3456
	ds_write_b32 v30, v25 offset:3600
	ds_write_b32 v30, v26 offset:3744
	ds_write_b32 v30, v27 offset:3888
	ds_write_b32 v30, v36 offset:4032
	ds_write_b32 v30, v28 offset:4176
	ds_write_b32 v30, v29 offset:4320
	ds_write_b32 v30, v35 offset:4464

; DI void dn_prep_item(const Params& p, int l, int item, int next_item, u32x4 (&pre)[12], unsigned char* lds, int tid) {
;     ...
;         {
;             const int c = tid & 127, rg = tid >> 7;
;             float xt[32];
; #pragma unroll
;             for (int k = 0; k < 32; ++k) xt[k] = XS[k * 129 + c];
; #pragma unroll
;             for (int ii = 0; ii < 8; ++ii) { const int i = rg * 8 + ii; float a0 = XS[(32 + i) * 129 + c], a1 = 0.f;
; #pragma unroll
;                 for (int k = 0; k < 32; k += 2) { a0 -= Zs[i * 33 + k] * xt[k]; a1 -= Zs[i * 33 + k + 1] * xt[k + 1]; }
;                 XS[(32 + i) * 129 + c] = a0 + a1; }
.LBB0_503:
	s_or_b64 exec, exec, s[8:9]
	v_ashrrev_i32_e32 v35, 4, v54
	v_and_b32_e32 v2, 0x7f, v54
	v_and_b32_e32 v38, -8, v35
	s_movk_i32 s12, 0x204
	v_lshl_add_u32 v36, v2, 2, v50
	v_mul_lo_u32 v40, v38, s12
	s_movk_i32 s5, 0x84
	v_add_u32_e32 v41, v36, v40
	v_mad_u64_u32 v[38:39], s[6:7], v38, s5, v[52:53]
	s_waitcnt lgkmcnt(0)
	s_barrier
	v_lshrrev_b32_e32 v38, 7, v54
	v_mul_u32_u24_e32 v38, 0x480, v38
	v_add_u32_e32 v38, v38, v52
	ds_read2_b32 v[32:33], v36 offset1:129
	v_add_u32_e32 v39, 0x400, v36
	ds_read2_b32 v[30:31], v39 offset0:2 offset1:131
	v_add_u32_e32 v39, 0x800, v36
	ds_read2_b32 v[28:29], v39 offset0:4 offset1:133
	v_add_u32_e32 v39, 0xc00, v36
	ds_read2_b32 v[26:27], v39 offset0:6 offset1:135
	v_add_u32_e32 v39, 0x1000, v36
	ds_read2_b32 v[24:25], v39 offset0:8 offset1:137
	v_add_u32_e32 v39, 0x1400, v36
	ds_read2_b32 v[22:23], v39 offset0:10 offset1:139
	v_add_u32_e32 v39, 0x1800, v36
	ds_read2_b32 v[20:21], v39 offset0:12 offset1:141
	v_add_u32_e32 v39, 0x1c00, v36
	ds_read2_b32 v[18:19], v39 offset0:14 offset1:143
	v_add_u32_e32 v39, 0x2000, v36
	ds_read2_b32 v[16:17], v39 offset0:16 offset1:145
	v_add_u32_e32 v39, 0x2400, v36
	ds_read2_b32 v[14:15], v39 offset0:18 offset1:147
	v_add_u32_e32 v39, 0x2800, v36
	ds_read2_b32 v[12:13], v39 offset0:20 offset1:149
	v_add_u32_e32 v39, 0x2c00, v36
	ds_read2_b32 v[10:11], v39 offset0:22 offset1:151
	v_add_u32_e32 v39, 0x3000, v36
	ds_read2_b32 v[8:9], v39 offset0:24 offset1:153
	v_add_u32_e32 v39, 0x3400, v36
	ds_read2_b32 v[6:7], v39 offset0:26 offset1:155
	v_add_u32_e32 v39, 0x3800, v36
	ds_read2_b32 v[4:5], v39 offset0:28 offset1:157
	v_add_u32_e32 v39, 0x3c00, v36
	ds_read2_b32 v[2:3], v39 offset0:30 offset1:159
	ds_read_b32 v244, v41 offset:16512
	ds_read_b32 v245, v41 offset:17028
	ds_read_b32 v246, v41 offset:17544
	ds_read_b32 v247, v41 offset:18060
	ds_read_b32 v248, v41 offset:18576
	ds_read_b32 v249, v41 offset:19092
	ds_read_b32 v250, v41 offset:19608
	ds_read_b32 v251, v41 offset:20124
	ds_read_b128 v[212:215], v38 offset:0
	ds_read_b128 v[216:219], v38 offset:16
	ds_read_b128 v[220:223], v38 offset:32
	ds_read_b128 v[224:227], v38 offset:48
	ds_read_b128 v[228:231], v38 offset:64
	ds_read_b128 v[232:235], v38 offset:80
	ds_read_b128 v[236:239], v38 offset:96
	ds_read_b128 v[240:243], v38 offset:112
	ds_read_b128 v[126:129], v38 offset:144
	ds_read_b128 v[130:133], v38 offset:160
	ds_read_b128 v[134:137], v38 offset:176
	ds_read_b128 v[138:141], v38 offset:192
	ds_read_b128 v[154:157], v38 offset:208
	ds_read_b128 v[188:191], v38 offset:224
	ds_read_b128 v[192:195], v38 offset:240
	ds_read_b128 v[196:199], v38 offset:256
	s_waitcnt lgkmcnt(8)
	v_fma_f32 v244, -v32, v212, v244
	v_fma_f32 v252, -v33, v213, 0
	v_fma_f32 v244, -v30, v214, v244
	v_fma_f32 v252, -v31, v215, v252
	v_fma_f32 v244, -v28, v216, v244
	v_fma_f32 v252, -v29, v217, v252
	v_fma_f32 v244, -v26, v218, v244
	v_fma_f32 v252, -v27, v219, v252
	v_fma_f32 v244, -v24, v220, v244
	v_fma_f32 v252, -v25, v221, v252
	v_fma_f32 v244, -v22, v222, v244
	v_fma_f32 v252, -v23, v223, v252
	v_fma_f32 v244, -v20, v224, v244
	v_fma_f32 v252, -v21, v225, v252
	v_fma_f32 v244, -v18, v226, v244
	v_fma_f32 v252, -v19, v227, v252
	v_fma_f32 v244, -v16, v228, v244
	v_fma_f32 v252, -v17, v229, v252
	v_fma_f32 v244, -v14, v230, v244
	v_fma_f32 v252, -v15, v231, v252
	v_fma_f32 v244, -v12, v232, v244
	v_fma_f32 v252, -v13, v233, v252
	v_fma_f32 v244, -v10, v234, v244
	v_fma_f32 v252, -v11, v235, v252
	v_fma_f32 v244, -v8, v236, v244
	v_fma_f32 v252, -v9, v237, v252
	v_fma_f32 v244, -v6, v238, v244
	v_fma_f32 v252, -v7, v239, v252
	v_fma_f32 v244, -v4, v240, v244
	v_fma_f32 v252, -v5, v241, v252
	v_fma_f32 v244, -v2, v242, v244
	v_fma_f32 v252, -v3, v243, v252
	v_add_f32_e32 v244, v244, v252
	ds_write_b32 v41, v244 offset:16512
	ds_read_b128 v[212:215], v38 offset:288
	ds_read_b128 v[216:219], v38 offset:304
	ds_read_b128 v[220:223], v38 offset:320
	ds_read_b128 v[224:227], v38 offset:336
	ds_read_b128 v[228:231], v38 offset:352
	ds_read_b128 v[232:235], v38 offset:368
	ds_read_b128 v[236:239], v38 offset:384
	ds_read_b128 v[240:243], v38 offset:400
	s_waitcnt lgkmcnt(9)
	v_fma_f32 v245, -v32, v126, v245
	v_fma_f32 v253, -v33, v127, 0
	v_fma_f32 v245, -v30, v128, v245
	v_fma_f32 v253, -v31, v129, v253
	v_fma_f32 v245, -v28, v130, v245
	v_fma_f32 v253, -v29, v131, v253
	v_fma_f32 v245, -v26, v132, v245
	v_fma_f32 v253, -v27, v133, v253
	v_fma_f32 v245, -v24, v134, v245
	v_fma_f32 v253, -v25, v135, v253
	v_fma_f32 v245, -v22, v136, v245
	v_fma_f32 v253, -v23, v137, v253
	v_fma_f32 v245, -v20, v138, v245
	v_fma_f32 v253, -v21, v139, v253
	v_fma_f32 v245, -v18, v140, v245
	v_fma_f32 v253, -v19, v141, v253
	v_fma_f32 v245, -v16, v154, v245
	v_fma_f32 v253, -v17, v155, v253
	v_fma_f32 v245, -v14, v156, v245
	v_fma_f32 v253, -v15, v157, v253
	v_fma_f32 v245, -v12, v188, v245
	v_fma_f32 v253, -v13, v189, v253
	v_fma_f32 v245, -v10, v190, v245
	v_fma_f32 v253, -v11, v191, v253
	v_fma_f32 v245, -v8, v192, v245
	v_fma_f32 v253, -v9, v193, v253
	v_fma_f32 v245, -v6, v194, v245
	v_fma_f32 v253, -v7, v195, v253
	v_fma_f32 v245, -v4, v196, v245
	v_fma_f32 v253, -v5, v197, v253
	v_fma_f32 v245, -v2, v198, v245
	v_fma_f32 v253, -v3, v199, v253
	v_add_f32_e32 v245, v245, v253
	ds_write_b32 v41, v245 offset:17028
	ds_read_b128 v[126:129], v38 offset:432
	ds_read_b128 v[130:133], v38 offset:448
	ds_read_b128 v[134:137], v38 offset:464
	ds_read_b128 v[138:141], v38 offset:480
	ds_read_b128 v[154:157], v38 offset:496
	ds_read_b128 v[188:191], v38 offset:512
	ds_read_b128 v[192:195], v38 offset:528
	ds_read_b128 v[196:199], v38 offset:544
	s_waitcnt lgkmcnt(9)
; DI void dn_prep_item(const Params& p, int l, int item, int next_item, u32x4 (&pre)[12], unsigned char* lds, int tid) {
;     ...
;             for (int ii = 0; ii < 8; ++ii) { const int i = rg * 8 + ii; float a0 = XS[(32 + i) * 129 + c], a1 = 0.f;
; #pragma unroll
;                 for (int k = 0; k < 32; k += 2) { a0 -= Zs[i * 33 + k] * xt[k]; a1 -= Zs[i * 33 + k + 1] * xt[k + 1]; }
;                 XS[(32 + i) * 129 + c] = a0 + a1; }
	v_fma_f32 v246, -v32, v212, v246
	v_fma_f32 v252, -v33, v213, 0
	v_fma_f32 v246, -v30, v214, v246
	v_fma_f32 v252, -v31, v215, v252
	v_fma_f32 v246, -v28, v216, v246
	v_fma_f32 v252, -v29, v217, v252
	v_fma_f32 v246, -v26, v218, v246
	v_fma_f32 v252, -v27, v219, v252
	v_fma_f32 v246, -v24, v220, v246
	v_fma_f32 v252, -v25, v221, v252
	v_fma_f32 v246, -v22, v222, v246
	v_fma_f32 v252, -v23, v223, v252
	v_fma_f32 v246, -v20, v224, v246
	v_fma_f32 v252, -v21, v225, v252
	v_fma_f32 v246, -v18, v226, v246
	v_fma_f32 v252, -v19, v227, v252
	v_fma_f32 v246, -v16, v228, v246
	v_fma_f32 v252, -v17, v229, v252
	v_fma_f32 v246, -v14, v230, v246
	v_fma_f32 v252, -v15, v231, v252
	v_fma_f32 v246, -v12, v232, v246
	v_fma_f32 v252, -v13, v233, v252
	v_fma_f32 v246, -v10, v234, v246
	v_fma_f32 v252, -v11, v235, v252
	v_fma_f32 v246, -v8, v236, v246
	v_fma_f32 v252, -v9, v237, v252
	v_fma_f32 v246, -v6, v238, v246
	v_fma_f32 v252, -v7, v239, v252
	v_fma_f32 v246, -v4, v240, v246
	v_fma_f32 v252, -v5, v241, v252
	v_fma_f32 v246, -v2, v242, v246
	v_fma_f32 v252, -v3, v243, v252
	v_add_f32_e32 v246, v246, v252
	ds_write_b32 v41, v246 offset:17544
	ds_read_b128 v[212:215], v38 offset:576
	ds_read_b128 v[216:219], v38 offset:592
	ds_read_b128 v[220:223], v38 offset:608
	ds_read_b128 v[224:227], v38 offset:624
	ds_read_b128 v[228:231], v38 offset:640
	ds_read_b128 v[232:235], v38 offset:656
	ds_read_b128 v[236:239], v38 offset:672
	ds_read_b128 v[240:243], v38 offset:688
	s_waitcnt lgkmcnt(9)
	v_fma_f32 v247, -v32, v126, v247
	v_fma_f32 v253, -v33, v127, 0
	v_fma_f32 v247, -v30, v128, v247
	v_fma_f32 v253, -v31, v129, v253
	v_fma_f32 v247, -v28, v130, v247
	v_fma_f32 v253, -v29, v131, v253
	v_fma_f32 v247, -v26, v132, v247
	v_fma_f32 v253, -v27, v133, v253
	v_fma_f32 v247, -v24, v134, v247
	v_fma_f32 v253, -v25, v135, v253
	v_fma_f32 v247, -v22, v136, v247
	v_fma_f32 v253, -v23, v137, v253
	v_fma_f32 v247, -v20, v138, v247
	v_fma_f32 v253, -v21, v139, v253
	v_fma_f32 v247, -v18, v140, v247
	v_fma_f32 v253, -v19, v141, v253
	v_fma_f32 v247, -v16, v154, v247
	v_fma_f32 v253, -v17, v155, v253
	v_fma_f32 v247, -v14, v156, v247
	v_fma_f32 v253, -v15, v157, v253
	v_fma_f32 v247, -v12, v188, v247
	v_fma_f32 v253, -v13, v189, v253
	v_fma_f32 v247, -v10, v190, v247
	v_fma_f32 v253, -v11, v191, v253
	v_fma_f32 v247, -v8, v192, v247
	v_fma_f32 v253, -v9, v193, v253
	v_fma_f32 v247, -v6, v194, v247
	v_fma_f32 v253, -v7, v195, v253
	v_fma_f32 v247, -v4, v196, v247
	v_fma_f32 v253, -v5, v197, v253
	v_fma_f32 v247, -v2, v198, v247
	v_fma_f32 v253, -v3, v199, v253
	v_add_f32_e32 v247, v247, v253
	ds_write_b32 v41, v247 offset:18060
	ds_read_b128 v[126:129], v38 offset:720
	ds_read_b128 v[130:133], v38 offset:736
	ds_read_b128 v[134:137], v38 offset:752
	ds_read_b128 v[138:141], v38 offset:768
	ds_read_b128 v[154:157], v38 offset:784
	ds_read_b128 v[188:191], v38 offset:800
	ds_read_b128 v[192:195], v38 offset:816
	ds_read_b128 v[196:199], v38 offset:832
	s_waitcnt lgkmcnt(9)
	v_fma_f32 v248, -v32, v212, v248
	v_fma_f32 v252, -v33, v213, 0
	v_fma_f32 v248, -v30, v214, v248
	v_fma_f32 v252, -v31, v215, v252
	v_fma_f32 v248, -v28, v216, v248
	v_fma_f32 v252, -v29, v217, v252
	v_fma_f32 v248, -v26, v218, v248
	v_fma_f32 v252, -v27, v219, v252
	v_fma_f32 v248, -v24, v220, v248
	v_fma_f32 v252, -v25, v221, v252
	v_fma_f32 v248, -v22, v222, v248
	v_fma_f32 v252, -v23, v223, v252
	v_fma_f32 v248, -v20, v224, v248
	v_fma_f32 v252, -v21, v225, v252
	v_fma_f32 v248, -v18, v226, v248
	v_fma_f32 v252, -v19, v227, v252
	v_fma_f32 v248, -v16, v228, v248
	v_fma_f32 v252, -v17, v229, v252
	v_fma_f32 v248, -v14, v230, v248
	v_fma_f32 v252, -v15, v231, v252
	v_fma_f32 v248, -v12, v232, v248
	v_fma_f32 v252, -v13, v233, v252
	v_fma_f32 v248, -v10, v234, v248
	v_fma_f32 v252, -v11, v235, v252
	v_fma_f32 v248, -v8, v236, v248
	v_fma_f32 v252, -v9, v237, v252
	v_fma_f32 v248, -v6, v238, v248
	v_fma_f32 v252, -v7, v239, v252
	v_fma_f32 v248, -v4, v240, v248
	v_fma_f32 v252, -v5, v241, v252
	v_fma_f32 v248, -v2, v242, v248
	v_fma_f32 v252, -v3, v243, v252
	v_add_f32_e32 v248, v248, v252
	ds_write_b32 v41, v248 offset:18576
	ds_read_b128 v[212:215], v38 offset:864
	ds_read_b128 v[216:219], v38 offset:880
	ds_read_b128 v[220:223], v38 offset:896
	ds_read_b128 v[224:227], v38 offset:912
	ds_read_b128 v[228:231], v38 offset:928
	ds_read_b128 v[232:235], v38 offset:944
	ds_read_b128 v[236:239], v38 offset:960
	ds_read_b128 v[240:243], v38 offset:976
	s_waitcnt lgkmcnt(9)
	v_fma_f32 v249, -v32, v126, v249
	v_fma_f32 v253, -v33, v127, 0
	v_fma_f32 v249, -v30, v128, v249
	v_fma_f32 v253, -v31, v129, v253
	v_fma_f32 v249, -v28, v130, v249
	v_fma_f32 v253, -v29, v131, v253
	v_fma_f32 v249, -v26, v132, v249
	v_fma_f32 v253, -v27, v133, v253
	v_fma_f32 v249, -v24, v134, v249
	v_fma_f32 v253, -v25, v135, v253
	v_fma_f32 v249, -v22, v136, v249
	v_fma_f32 v253, -v23, v137, v253
	v_fma_f32 v249, -v20, v138, v249
	v_fma_f32 v253, -v21, v139, v253
	v_fma_f32 v249, -v18, v140, v249
	v_fma_f32 v253, -v19, v141, v253
	v_fma_f32 v249, -v16, v154, v249
	v_fma_f32 v253, -v17, v155, v253
	v_fma_f32 v249, -v14, v156, v249
	v_fma_f32 v253, -v15, v157, v253
	v_fma_f32 v249, -v12, v188, v249
	v_fma_f32 v253, -v13, v189, v253
	v_fma_f32 v249, -v10, v190, v249
	v_fma_f32 v253, -v11, v191, v253
	v_fma_f32 v249, -v8, v192, v249
	v_fma_f32 v253, -v9, v193, v253
	v_fma_f32 v249, -v6, v194, v249
	v_fma_f32 v253, -v7, v195, v253
	v_fma_f32 v249, -v4, v196, v249
	v_fma_f32 v253, -v5, v197, v253
	v_fma_f32 v249, -v2, v198, v249
	v_fma_f32 v253, -v3, v199, v253
	v_add_f32_e32 v249, v249, v253
	ds_write_b32 v41, v249 offset:19092
	ds_read_b128 v[126:129], v38 offset:1008
	ds_read_b128 v[130:133], v38 offset:1024
	ds_read_b128 v[134:137], v38 offset:1040
	ds_read_b128 v[138:141], v38 offset:1056
	ds_read_b128 v[154:157], v38 offset:1072
	ds_read_b128 v[188:191], v38 offset:1088
	ds_read_b128 v[192:195], v38 offset:1104
	ds_read_b128 v[196:199], v38 offset:1120
	s_waitcnt lgkmcnt(9)
; DI unsigned pk2(float lo, float hi) { f32x2_t v = {lo, hi}; bf16x2_t b = __builtin_convertvector(v, bf16x2_t); return __builtin_bit_cast(unsigned, b); }
; DI void dn_prep_item(const Params& p, int l, int item, int next_item, u32x4 (&pre)[12], unsigned char* lds, int tid) {
;     ...
;             for (int ii = 0; ii < 8; ++ii) { const int i = rg * 8 + ii; float a0 = XS[(32 + i) * 129 + c], a1 = 0.f;
; #pragma unroll
;                 for (int k = 0; k < 32; k += 2) { a0 -= Zs[i * 33 + k] * xt[k]; a1 -= Zs[i * 33 + k + 1] * xt[k + 1]; }
;                 XS[(32 + i) * 129 + c] = a0 + a1; }
;     ...
;     __syncthreads();
;     dn_prep_fetch(p, next_item < 2048 ? next_item : item, tid, pre);
;     {
;         const int chunk = (b * 8 + h) * 32 + n; unsigned char* base = p.ws + OFF_U + (size_t)chunk * PREP_CHUNK_BYTES;
;         const int f = tid >> 6, m = f >> 1, s = f & 1, r = lane & 15, g = lane >> 4, row = 16 * m + r, c0 = 32 * s + 4 * g, c1 = c0 + 16;
;         u32x4 w;
;         { const float* a = XS + row * 129 + 64; w.x = pk2(a[c0], a[c0 + 1]); w.y = pk2(a[c0 + 2], a[c0 + 3]); w.z = pk2(a[c1], a[c1 + 1]); w.w = pk2(a[c1 + 2], a[c1 + 3]); *(u32x4*)(base + (size_t)tid * 16) = w; }
; #pragma unroll
;         for (int q = 0; q < 2; ++q) { const int idx = tid * 2 + q, wm = idx >> 6, ln = idx & 63, vv = 16 * (wm >> 2) + (ln & 15), r0 = 16 * (wm & 3) + 4 * (ln >> 4);
;             u32x2 o; o.x = pk2(XS[r0 * 129 + vv], XS[(r0 + 1) * 129 + vv]); o.y = pk2(XS[(r0 + 2) * 129 + vv], XS[(r0 + 3) * 129 + vv]); *(u32x2*)(base + 32768 + (size_t)idx * 8) = o; }
;         if (tid == 0) ((float*)(p.ws + OFF_CD))[chunk] = EGs[63];
	v_fma_f32 v250, -v32, v212, v250
	v_fma_f32 v252, -v33, v213, 0
	v_fma_f32 v250, -v30, v214, v250
	v_fma_f32 v252, -v31, v215, v252
	v_fma_f32 v250, -v28, v216, v250
	v_fma_f32 v252, -v29, v217, v252
	v_fma_f32 v250, -v26, v218, v250
	v_fma_f32 v252, -v27, v219, v252
	v_fma_f32 v250, -v24, v220, v250
	v_fma_f32 v252, -v25, v221, v252
	v_fma_f32 v250, -v22, v222, v250
	v_fma_f32 v252, -v23, v223, v252
	v_fma_f32 v250, -v20, v224, v250
	v_fma_f32 v252, -v21, v225, v252
	v_fma_f32 v250, -v18, v226, v250
	v_fma_f32 v252, -v19, v227, v252
	v_fma_f32 v250, -v16, v228, v250
	v_fma_f32 v252, -v17, v229, v252
	v_fma_f32 v250, -v14, v230, v250
	v_fma_f32 v252, -v15, v231, v252
	v_fma_f32 v250, -v12, v232, v250
	v_fma_f32 v252, -v13, v233, v252
	v_fma_f32 v250, -v10, v234, v250
	v_fma_f32 v252, -v11, v235, v252
	v_fma_f32 v250, -v8, v236, v250
	v_fma_f32 v252, -v9, v237, v252
	v_fma_f32 v250, -v6, v238, v250
	v_fma_f32 v252, -v7, v239, v252
	v_fma_f32 v250, -v4, v240, v250
	v_fma_f32 v252, -v5, v241, v252
	v_fma_f32 v250, -v2, v242, v250
	v_fma_f32 v252, -v3, v243, v252
	v_add_f32_e32 v250, v250, v252
	ds_write_b32 v41, v250 offset:19608
	s_waitcnt lgkmcnt(1)
	v_fma_f32 v251, -v32, v126, v251
	v_fma_f32 v253, -v33, v127, 0
	v_fma_f32 v251, -v30, v128, v251
	v_fma_f32 v253, -v31, v129, v253
	v_fma_f32 v251, -v28, v130, v251
	v_fma_f32 v253, -v29, v131, v253
	v_fma_f32 v251, -v26, v132, v251
	v_fma_f32 v253, -v27, v133, v253
	v_fma_f32 v251, -v24, v134, v251
	v_fma_f32 v253, -v25, v135, v253
	v_fma_f32 v251, -v22, v136, v251
	v_fma_f32 v253, -v23, v137, v253
	v_fma_f32 v251, -v20, v138, v251
	v_fma_f32 v253, -v21, v139, v253
	v_fma_f32 v251, -v18, v140, v251
	v_fma_f32 v253, -v19, v141, v253
	v_fma_f32 v251, -v16, v154, v251
	v_fma_f32 v253, -v17, v155, v253
	v_fma_f32 v251, -v14, v156, v251
	v_fma_f32 v253, -v15, v157, v253
	v_fma_f32 v251, -v12, v188, v251
	v_fma_f32 v253, -v13, v189, v253
	v_fma_f32 v251, -v10, v190, v251
	v_fma_f32 v253, -v11, v191, v253
	v_fma_f32 v251, -v8, v192, v251
	v_fma_f32 v253, -v9, v193, v253
	v_fma_f32 v251, -v6, v194, v251
	v_fma_f32 v253, -v7, v195, v253
	v_fma_f32 v251, -v4, v196, v251
	v_fma_f32 v253, -v5, v197, v253
	v_fma_f32 v251, -v2, v198, v251
	v_fma_f32 v253, -v3, v199, v253
	v_add_f32_e32 v251, v251, v253
	ds_write_b32 v41, v251 offset:20124
	s_add_i32 s4, s42, s33
	s_cmpk_gt_i32 s4, 0x7ff
	v_and_b32_e32 v66, -16, v77
	v_lshl_add_u64 v[62:63], s[26:27], 0, v[58:59]
	v_or_b32_e32 v58, v66, v61
	v_ashrrev_i32_e32 v57, 31, v56
	s_cselect_b64 s[6:7], -1, 0
	s_cmpk_lt_i32 s4, 0x800
	s_cselect_b32 s5, s4, s42
	s_lshl_b32 s8, s5, 3
	s_lshl_b32 s5, s5, 7
	s_and_b32 s10, s8, 0x7c0
	s_and_b32 s11, s8, 0xfffff800
	s_and_b32 s5, s5, 0x380
	s_add_u32 s8, s29, s5
	s_addc_u32 s9, s40, 0
	v_mov_b32_e32 v35, v165
	s_movk_i32 s5, 0xc00
	v_add_u32_e32 v10, s10, v77
	v_max_i32_e32 v10, 0, v10
	v_add_u32_e32 v10, s11, v10
	v_add3_u32 v8, s10, -3, v77
	v_max_i32_e32 v4, 0, v8
	v_max_i32_e32 v6, -1, v8
	v_max_i32_e32 v8, -2, v8
	v_lshl_add_u64 v[2:3], s[8:9], 0, v[34:35]
	v_add_u32_e32 v4, s11, v4
	v_add3_u32 v6, v6, s11, 1
	v_add3_u32 v8, v8, s11, 2
	v_mad_i64_i32 v[4:5], s[8:9], v4, s5, v[2:3]
	v_mad_i64_i32 v[6:7], s[8:9], v6, s5, v[2:3]
	v_mad_i64_i32 v[8:9], s[8:9], v8, s5, v[2:3]
	v_mad_i64_i32 v[2:3], s[8:9], v10, s5, v[2:3]
	s_waitcnt lgkmcnt(0)
	s_barrier
	global_load_dwordx4 v[46:49], v[4:5], off
	global_load_dwordx4 v[42:45], v[6:7], off
	global_load_dwordx4 v[38:41], v[8:9], off
	global_load_dwordx4 v[34:37], v[2:3], off
	global_load_dwordx4 v[30:33], v[4:5], off offset:1024
	global_load_dwordx4 v[26:29], v[6:7], off offset:1024
	global_load_dwordx4 v[22:25], v[8:9], off offset:1024
	global_load_dwordx4 v[18:21], v[2:3], off offset:1024
	global_load_dwordx4 v[14:17], v[4:5], off offset:2048
	global_load_dwordx4 v[10:13], v[6:7], off offset:2048
	s_nop 0
	global_load_dwordx4 v[6:9], v[8:9], off offset:2048
	s_nop 0
	global_load_dwordx4 v[2:5], v[2:3], off offset:2048
	v_mad_u64_u32 v[58:59], s[8:9], v58, s12, v[50:51]
	v_lshlrev_b32_e32 v59, 7, v60
	v_and_b32_e32 v59, 0x80, v59
	v_and_b32_e32 v60, 48, v54
	v_add3_u32 v64, v58, v59, v60
	ds_read2_b32 v[58:59], v64 offset0:64 offset1:65
	ds_read2_b32 v[60:61], v64 offset0:66 offset1:67
	s_waitcnt lgkmcnt(1)
	v_cvt_pk_bf16_f32 v58, v58, v59
	s_waitcnt lgkmcnt(0)
	v_cvt_pk_bf16_f32 v59, v60, v61
	ds_read2_b32 v[60:61], v64 offset0:80 offset1:81
	ds_read2_b32 v[64:65], v64 offset0:82 offset1:83
	s_waitcnt lgkmcnt(1)
	v_cvt_pk_bf16_f32 v60, v60, v61
	s_waitcnt lgkmcnt(0)
	v_cvt_pk_bf16_f32 v61, v64, v65
	v_lshl_add_u64 v[64:65], v[54:55], 4, v[62:63]
	v_lshrrev_b32_e32 v55, 1, v54
	global_store_dwordx4 v[64:65], v[58:61], off
	v_and_b32_e32 v55, 48, v55
	s_nop 0
	v_lshrrev_b32_e32 v58, 2, v56
	v_and_or_b32 v55, v58, 12, v55
	v_mul_u32_u24_e32 v55, 0x81, v55
	v_and_b32_e32 v58, 14, v56
	v_lshl_add_u32 v58, v58, 2, v50
	v_lshlrev_b32_e32 v59, 2, v66
	v_lshlrev_b32_e32 v55, 2, v55
	v_add3_u32 v55, v58, v59, v55
	ds_read2_b32 v[60:61], v55 offset1:1
	ds_read2_b32 v[64:65], v55 offset0:129 offset1:130
	v_add_u32_e32 v59, 0x408, v55
	v_add_u32_e32 v55, 0x60c, v55
	ds_read2_b32 v[66:67], v59 offset1:1
	ds_read2_b32 v[78:79], v55 offset1:1
	v_lshl_add_u64 v[56:57], v[56:57], 3, v[62:63]
	v_add_co_u32_e32 v56, vcc, 0x8000, v56
	s_waitcnt lgkmcnt(2)
	v_cvt_pk_bf16_f32 v58, v60, v64
	v_addc_co_u32_e32 v57, vcc, 0, v57, vcc
	s_waitcnt lgkmcnt(0)
	v_cvt_pk_bf16_f32 v59, v66, v78
	v_cvt_pk_bf16_f32 v60, v61, v65
	v_cvt_pk_bf16_f32 v61, v67, v79
	v_cmp_eq_u32_e32 vcc, 0, v54
	global_store_dwordx4 v[56:57], v[58:61], off
	s_and_saveexec_b64 s[8:9], vcc
	s_cbranch_execz .LBB0_280
	ds_read_b32 v54, v76
	v_lshl_add_u64 v[0:1], v[0:1], 2, s[38:39]
	s_waitcnt lgkmcnt(0)
	global_store_dword v[0:1], v54, off
	s_branch .LBB0_280
